# first phase boundary uses the XCD-hierarchical barrier instead of the cooperative-groups grid sync
# speedup vs baseline: 1.0076x; 1.0076x over previous
.LBB0_89:
	s_cmp_eq_u32 s71, 1
	s_cbranch_scc1 .LBB0_153
	s_cmp_lg_u32 s70, 0
	s_waitcnt vmcnt(0)
	s_barrier
	s_mov_b64 s[2:3], exec
	v_readlane_b32 s4, v253, 6
	v_readlane_b32 s5, v253, 7
	s_and_b64 s[4:5], s[2:3], s[4:5]
	s_mov_b64 exec, s[4:5]
	s_cbranch_execz .LBB0_140
	v_mov_b32_e32 v1, 0x12000
	s_waitcnt vmcnt(0) expcnt(0) lgkmcnt(0)
	ds_read_b32 v3, v1
	v_mov_b32_e32 v1, 0x12004
	ds_read_b32 v1, v1
	s_waitcnt lgkmcnt(1)
	v_cmp_ne_u32_e32 vcc, 0, v3
	s_cbranch_vccnz .LBB0_108
	s_mov_b64 s[4:5], s[80:81]
	s_mul_i32 s1, s5, s0
	s_mul_i32 s1, s1, s4
	s_add_u32 s4, s68, 0x38e00200
	s_addc_u32 s5, s69, 0
	s_add_u32 s6, s68, 0x38e00400
	s_addc_u32 s7, s69, 0
	s_add_u32 s8, s68, 0x38e00500
	s_addc_u32 s9, s69, 0
	s_add_u32 s10, s68, 0x38e00600
	s_addc_u32 s11, s69, 0
	s_add_u32 s12, s68, 0x38e00700
	s_addc_u32 s13, s69, 0
	s_add_u32 s14, s68, 0x38e00800
	s_addc_u32 s15, s69, 0
	s_add_u32 s16, s68, 0x38e00900
	s_addc_u32 s17, s69, 0
	s_add_u32 s18, s68, 0x38e00a00
	s_addc_u32 s19, s69, 0
	s_add_u32 s20, s68, 0x38e00b00
	s_addc_u32 s21, s69, 0
	s_add_u32 s22, s68, 0x38e00c00
	s_addc_u32 s23, s69, 0
	s_add_u32 s24, s68, 0x38e00d00
	s_addc_u32 s25, s69, 0
	s_add_u32 s26, s68, 0x38e00e00
	s_addc_u32 s27, s69, 0
	s_add_u32 s28, s68, 0x38e00f00
	s_addc_u32 s29, s69, 0
	s_add_u32 s30, s68, 0x38e01000
	s_addc_u32 s31, s69, 0
	s_add_u32 s34, s68, 0x38e01100
	s_addc_u32 s35, s69, 0
	s_add_u32 s36, s68, 0x38e01200
	s_addc_u32 s37, s69, 0
	s_add_u32 s38, s68, 0x38e01300
	s_addc_u32 s39, s69, 0
	s_mov_b32 s33, 1
	v_mov_b32_e32 v17, 0
	s_branch .LBB0_95
